# ph9 quarter mode: stage loads of unused operand halves replaced by one-dword dummy loads (same vmcnt accounting)
# baseline (speedup 1.0000x reference)
.LBB0_253:
	s_add_i32 s82, s18, 2
	s_cmp_eq_u32 s70, s18
	s_cselect_b32 s18, s49, s78
	s_cselect_b32 s19, s47, s79
	s_cselect_b32 s56, s73, s80
	s_cselect_b32 s57, s72, s81
	s_add_u32 s26, s18, 0x80
	s_addc_u32 s27, s19, 0
	s_add_i32 s83, 0, 0x10000
	v_add_u32_e32 v0, s83, v213
	s_add_i32 s86, 0, 0x14000
	ds_read_b128 v[130:133], v0
	ds_read_b128 v[134:137], v0 offset:1024
	ds_read_b128 v[138:141], v0 offset:2048
	ds_read_b128 v[142:145], v0 offset:3072
	v_add_u32_e32 v0, s86, v213
	ds_read_b128 v[146:149], v0
	ds_read_b128 v[150:153], v0 offset:1024
	ds_read_b128 v[154:157], v0 offset:2048
	ds_read_b128 v[158:161], v0 offset:3072
	s_add_u32 s84, s78, 0x3ff80
	s_addc_u32 s85, s79, 0
	ds_read_b128 v[162:165], v216
	ds_read_b128 v[166:169], v216 offset:1024
	ds_read_b128 v[194:197], v216 offset:2048
	ds_read_b128 v[198:201], v216 offset:3072
	ds_read_b128 v[202:205], v216 offset:4096
	ds_read_b128 v[206:209], v216 offset:5120
	ds_read_b128 v[218:221], v216 offset:6144
	ds_read_b128 v[222:225], v216 offset:7168
	s_add_i32 m0, s40, 0xc000
	v_lshl_add_u64 v[210:211], s[84:85], 0, v[172:173]
	s_cmp_lg_u32 s100, 0
	s_cbranch_scc1 .Lh9_d0
	global_load_lds_dwordx4 v[210:211], off
	s_branch .Lh9_e0
.Lh9_d0:
	global_load_dword v252, v1, s[84:85]
.Lh9_e0:
	v_lshl_add_u64 v[210:211], s[84:85], 0, v[170:171]
	s_add_i32 m0, s40, 0xe000
	s_nop 0
	s_cmp_lg_u32 s100, 0
	s_cbranch_scc1 .Lh9_d1
	global_load_lds_dwordx4 v[210:211], off
	s_branch .Lh9_e1

.Lh9_e1:
	s_waitcnt vmcnt(8)
	s_waitcnt lgkmcnt(0)
	s_barrier
	s_setprio 1
	s_waitcnt lgkmcnt(0)
	v_mfma_f32_16x16x32_bf16 v[126:129], v[130:133], v[162:165], v[126:129]
	v_mfma_f32_16x16x32_bf16 v[122:125], v[138:141], v[162:165], v[122:125]
	v_mfma_f32_16x16x32_bf16 v[110:113], v[130:133], v[194:197], v[110:113]
	v_mfma_f32_16x16x32_bf16 v[106:109], v[138:141], v[194:197], v[106:109]
	v_mfma_f32_16x16x32_bf16 v[94:97], v[130:133], v[202:205], v[94:97]
	v_mfma_f32_16x16x32_bf16 v[90:93], v[138:141], v[202:205], v[90:93]
	v_mfma_f32_16x16x32_bf16 v[78:81], v[130:133], v[218:221], v[78:81]
	v_mfma_f32_16x16x32_bf16 v[74:77], v[138:141], v[218:221], v[74:77]
	v_mfma_f32_16x16x32_bf16 v[126:129], v[134:137], v[166:169], v[126:129]
	v_mfma_f32_16x16x32_bf16 v[122:125], v[142:145], v[166:169], v[122:125]
	v_mfma_f32_16x16x32_bf16 v[110:113], v[134:137], v[198:201], v[110:113]
	v_mfma_f32_16x16x32_bf16 v[106:109], v[142:145], v[198:201], v[106:109]
	v_mfma_f32_16x16x32_bf16 v[94:97], v[134:137], v[206:209], v[94:97]
	v_mfma_f32_16x16x32_bf16 v[90:93], v[142:145], v[206:209], v[90:93]
	v_mfma_f32_16x16x32_bf16 v[78:81], v[134:137], v[222:225], v[78:81]
	v_mfma_f32_16x16x32_bf16 v[74:77], v[142:145], v[222:225], v[74:77]
	s_bitcmp1_b32 s100, 2
	s_cbranch_scc1 .Lh9_q0
	v_mfma_f32_16x16x32_bf16 v[118:121], v[146:149], v[162:165], v[118:121]
	v_mfma_f32_16x16x32_bf16 v[114:117], v[154:157], v[162:165], v[114:117]
	v_mfma_f32_16x16x32_bf16 v[102:105], v[146:149], v[194:197], v[102:105]
	v_mfma_f32_16x16x32_bf16 v[98:101], v[154:157], v[194:197], v[98:101]
	v_mfma_f32_16x16x32_bf16 v[86:89], v[146:149], v[202:205], v[86:89]
	v_mfma_f32_16x16x32_bf16 v[82:85], v[154:157], v[202:205], v[82:85]
	v_mfma_f32_16x16x32_bf16 v[70:73], v[146:149], v[218:221], v[70:73]
	v_mfma_f32_16x16x32_bf16 v[66:69], v[154:157], v[218:221], v[66:69]
	v_mfma_f32_16x16x32_bf16 v[118:121], v[150:153], v[166:169], v[118:121]
	v_mfma_f32_16x16x32_bf16 v[114:117], v[158:161], v[166:169], v[114:117]
	v_mfma_f32_16x16x32_bf16 v[102:105], v[150:153], v[198:201], v[102:105]
	v_mfma_f32_16x16x32_bf16 v[98:101], v[158:161], v[198:201], v[98:101]
	v_mfma_f32_16x16x32_bf16 v[86:89], v[150:153], v[206:209], v[86:89]
	v_mfma_f32_16x16x32_bf16 v[82:85], v[158:161], v[206:209], v[82:85]
	v_mfma_f32_16x16x32_bf16 v[70:73], v[150:153], v[222:225], v[70:73]
	v_mfma_f32_16x16x32_bf16 v[66:69], v[158:161], v[222:225], v[66:69]
.Lh9_q0:
	s_setprio 0
	s_barrier
	s_mov_b64 s[84:85], s[56:57]
	s_add_i32 s83, s83, s25
	ds_read_b128 v[162:165], v216 offset:16384
	ds_read_b128 v[166:169], v216 offset:17408
	ds_read_b128 v[194:197], v216 offset:18432
	ds_read_b128 v[198:201], v216 offset:19456
	ds_read_b128 v[202:205], v216 offset:20480
	ds_read_b128 v[206:209], v216 offset:21504
	ds_read_b128 v[218:221], v216 offset:22528
	ds_read_b128 v[222:225], v216 offset:23552
	s_mov_b32 m0, s83
	v_lshl_add_u64 v[210:211], s[84:85], 0, v[172:173]
	global_load_lds_dwordx4 v[210:211], off
	s_add_i32 m0, s83, 0x2000
	v_lshl_add_u64 v[210:211], s[84:85], 0, v[170:171]
	s_add_u32 s84, s56, 0x40000
	s_addc_u32 s85, s57, 0
	s_add_i32 s83, s86, s25
	global_load_lds_dwordx4 v[210:211], off
	s_mov_b32 m0, s83
	v_lshl_add_u64 v[210:211], s[84:85], 0, v[172:173]
	s_bitcmp1_b32 s100, 2
	s_cbranch_scc1 .Lh9_d4
	global_load_lds_dwordx4 v[210:211], off
	s_branch .Lh9_e4

.Lh9_e4:
	v_lshl_add_u64 v[210:211], s[84:85], 0, v[170:171]
	s_add_i32 m0, s83, 0x2000
	s_mov_b64 s[84:85], s[18:19]
	s_bitcmp1_b32 s100, 2
	s_cbranch_scc1 .Lh9_d5
	global_load_lds_dwordx4 v[210:211], off
	s_branch .Lh9_e5

.Lh9_e5:
	s_mov_b32 m0, s40
	v_lshl_add_u64 v[210:211], s[84:85], 0, v[172:173]
	global_load_lds_dwordx4 v[210:211], off
	v_lshl_add_u64 v[210:211], s[84:85], 0, v[170:171]
	s_mov_b32 m0, s41
	s_nop 0
	global_load_lds_dwordx4 v[210:211], off
	s_waitcnt vmcnt(8)
	s_waitcnt lgkmcnt(0)
	s_barrier
	s_setprio 1
	s_waitcnt lgkmcnt(0)
	s_cmp_lg_u32 s100, 0
	s_cbranch_scc1 .Lh9_m0
	v_mfma_f32_16x16x32_bf16 v[62:65], v[130:133], v[162:165], v[62:65]
	v_mfma_f32_16x16x32_bf16 v[58:61], v[138:141], v[162:165], v[58:61]
	v_mfma_f32_16x16x32_bf16 v[46:49], v[130:133], v[194:197], v[46:49]
	v_mfma_f32_16x16x32_bf16 v[42:45], v[138:141], v[194:197], v[42:45]
	v_mfma_f32_16x16x32_bf16 v[30:33], v[130:133], v[202:205], v[30:33]
	v_mfma_f32_16x16x32_bf16 v[26:29], v[138:141], v[202:205], v[26:29]
	v_mfma_f32_16x16x32_bf16 v[14:17], v[130:133], v[218:221], v[14:17]
	v_mfma_f32_16x16x32_bf16 v[10:13], v[138:141], v[218:221], v[10:13]
	v_mfma_f32_16x16x32_bf16 v[62:65], v[134:137], v[166:169], v[62:65]
	v_mfma_f32_16x16x32_bf16 v[58:61], v[142:145], v[166:169], v[58:61]
	v_mfma_f32_16x16x32_bf16 v[46:49], v[134:137], v[198:201], v[46:49]
	v_mfma_f32_16x16x32_bf16 v[42:45], v[142:145], v[198:201], v[42:45]
	v_mfma_f32_16x16x32_bf16 v[30:33], v[134:137], v[206:209], v[30:33]
	v_mfma_f32_16x16x32_bf16 v[26:29], v[142:145], v[206:209], v[26:29]
	v_mfma_f32_16x16x32_bf16 v[14:17], v[134:137], v[222:225], v[14:17]
	v_mfma_f32_16x16x32_bf16 v[10:13], v[142:145], v[222:225], v[10:13]
	v_mfma_f32_16x16x32_bf16 v[54:57], v[146:149], v[162:165], v[54:57]
	v_mfma_f32_16x16x32_bf16 v[50:53], v[154:157], v[162:165], v[50:53]
	v_mfma_f32_16x16x32_bf16 v[38:41], v[146:149], v[194:197], v[38:41]
	v_mfma_f32_16x16x32_bf16 v[34:37], v[154:157], v[194:197], v[34:37]
	v_mfma_f32_16x16x32_bf16 v[22:25], v[146:149], v[202:205], v[22:25]
	v_mfma_f32_16x16x32_bf16 v[18:21], v[154:157], v[202:205], v[18:21]
	v_mfma_f32_16x16x32_bf16 v[6:9], v[146:149], v[218:221], v[6:9]
	v_mfma_f32_16x16x32_bf16 v[2:5], v[154:157], v[218:221], v[2:5]
	v_mfma_f32_16x16x32_bf16 v[54:57], v[150:153], v[166:169], v[54:57]
	v_mfma_f32_16x16x32_bf16 v[50:53], v[158:161], v[166:169], v[50:53]
	v_mfma_f32_16x16x32_bf16 v[38:41], v[150:153], v[198:201], v[38:41]
	v_mfma_f32_16x16x32_bf16 v[34:37], v[158:161], v[198:201], v[34:37]
	v_mfma_f32_16x16x32_bf16 v[22:25], v[150:153], v[206:209], v[22:25]
	v_mfma_f32_16x16x32_bf16 v[18:21], v[158:161], v[206:209], v[18:21]
	v_mfma_f32_16x16x32_bf16 v[6:9], v[150:153], v[222:225], v[6:9]
	v_mfma_f32_16x16x32_bf16 v[2:5], v[158:161], v[222:225], v[2:5]
.Lh9_m0:
	s_setprio 0
	s_barrier
	s_add_i32 s83, 0, 0x18000
	v_add_u32_e32 v0, s83, v213
	s_add_i32 s84, 0, 0x1c000
	ds_read_b128 v[130:133], v0
	ds_read_b128 v[134:137], v0 offset:1024
	ds_read_b128 v[138:141], v0 offset:2048
	ds_read_b128 v[142:145], v0 offset:3072
	v_add_u32_e32 v0, s84, v213
	ds_read_b128 v[146:149], v0
	ds_read_b128 v[150:153], v0 offset:1024
	ds_read_b128 v[154:157], v0 offset:2048
	ds_read_b128 v[158:161], v0 offset:3072
	s_add_u32 s18, s18, 0x40000
	s_addc_u32 s19, s19, 0
	s_mov_b32 m0, s60
	ds_read_b128 v[162:165], v216 offset:32768
	ds_read_b128 v[166:169], v216 offset:33792
	ds_read_b128 v[194:197], v216 offset:34816
	ds_read_b128 v[198:201], v216 offset:35840
	ds_read_b128 v[202:205], v216 offset:36864
	ds_read_b128 v[206:209], v216 offset:37888
	ds_read_b128 v[218:221], v216 offset:38912
	ds_read_b128 v[222:225], v216 offset:39936
	s_nop 0
	v_lshl_add_u64 v[210:211], s[18:19], 0, v[172:173]
	s_cmp_lg_u32 s100, 0
	s_cbranch_scc1 .Lh9_d8
	global_load_lds_dwordx4 v[210:211], off
	s_branch .Lh9_e8
.Lh9_d8:
	global_load_dword v252, v1, s[18:19]
.Lh9_e8:
	v_lshl_add_u64 v[210:211], s[18:19], 0, v[170:171]
	s_mov_b32 m0, s61
	s_nop 0
	s_cmp_lg_u32 s100, 0
	s_cbranch_scc1 .Lh9_d9
	global_load_lds_dwordx4 v[210:211], off
	s_branch .Lh9_e9

.Lh9_q1:
	s_setprio 0
	s_barrier
	s_add_u32 s18, s56, 0x80
	s_addc_u32 s19, s57, 0
	s_add_i32 s83, s83, s25
	ds_read_b128 v[162:165], v216 offset:49152
	ds_read_b128 v[166:169], v216 offset:50176
	ds_read_b128 v[194:197], v216 offset:51200
	ds_read_b128 v[198:201], v216 offset:52224
	ds_read_b128 v[202:205], v216 offset:53248
	ds_read_b128 v[206:209], v216 offset:54272
	ds_read_b128 v[218:221], v216 offset:55296
	ds_read_b128 v[222:225], v216 offset:56320
	s_mov_b32 m0, s83
	v_lshl_add_u64 v[210:211], s[18:19], 0, v[172:173]
	global_load_lds_dwordx4 v[210:211], off
	s_add_i32 m0, s83, 0x2000
	v_lshl_add_u64 v[210:211], s[18:19], 0, v[170:171]
	s_add_u32 s18, s56, 0x40080
	s_addc_u32 s19, s57, 0
	s_add_i32 s56, s84, s25
	global_load_lds_dwordx4 v[210:211], off
	s_mov_b32 m0, s56
	v_lshl_add_u64 v[210:211], s[18:19], 0, v[172:173]
	s_bitcmp1_b32 s100, 2
	s_cbranch_scc1 .Lh9_d12
	global_load_lds_dwordx4 v[210:211], off
	s_branch .Lh9_e12

.Lh9_e12:
	v_lshl_add_u64 v[210:211], s[18:19], 0, v[170:171]
	s_add_i32 m0, s56, 0x2000
	s_nop 0
	s_bitcmp1_b32 s100, 2
	s_cbranch_scc1 .Lh9_d13
	global_load_lds_dwordx4 v[210:211], off
	s_branch .Lh9_e13

.Lh9_e13:
	s_mov_b32 m0, s68
	v_lshl_add_u64 v[210:211], s[26:27], 0, v[172:173]
	global_load_lds_dwordx4 v[210:211], off
	v_lshl_add_u64 v[210:211], s[26:27], 0, v[170:171]
	s_mov_b32 m0, s69
	s_nop 0
	global_load_lds_dwordx4 v[210:211], off
	s_waitcnt vmcnt(8)
	s_waitcnt lgkmcnt(0)
	s_barrier
	s_setprio 1
	s_waitcnt lgkmcnt(0)
	s_cmp_lg_u32 s100, 0
	s_cbranch_scc1 .Lh9_m1
	v_mfma_f32_16x16x32_bf16 v[62:65], v[130:133], v[162:165], v[62:65]
	v_mfma_f32_16x16x32_bf16 v[58:61], v[138:141], v[162:165], v[58:61]
	v_mfma_f32_16x16x32_bf16 v[46:49], v[130:133], v[194:197], v[46:49]
	v_mfma_f32_16x16x32_bf16 v[42:45], v[138:141], v[194:197], v[42:45]
	v_mfma_f32_16x16x32_bf16 v[30:33], v[130:133], v[202:205], v[30:33]
	v_mfma_f32_16x16x32_bf16 v[26:29], v[138:141], v[202:205], v[26:29]
	v_mfma_f32_16x16x32_bf16 v[14:17], v[130:133], v[218:221], v[14:17]
	v_mfma_f32_16x16x32_bf16 v[10:13], v[138:141], v[218:221], v[10:13]
	v_mfma_f32_16x16x32_bf16 v[62:65], v[134:137], v[166:169], v[62:65]
	v_mfma_f32_16x16x32_bf16 v[58:61], v[142:145], v[166:169], v[58:61]
	v_mfma_f32_16x16x32_bf16 v[46:49], v[134:137], v[198:201], v[46:49]
	v_mfma_f32_16x16x32_bf16 v[42:45], v[142:145], v[198:201], v[42:45]
	v_mfma_f32_16x16x32_bf16 v[30:33], v[134:137], v[206:209], v[30:33]
	v_mfma_f32_16x16x32_bf16 v[26:29], v[142:145], v[206:209], v[26:29]
	v_mfma_f32_16x16x32_bf16 v[14:17], v[134:137], v[222:225], v[14:17]
	v_mfma_f32_16x16x32_bf16 v[10:13], v[142:145], v[222:225], v[10:13]
	v_mfma_f32_16x16x32_bf16 v[54:57], v[146:149], v[162:165], v[54:57]
	v_mfma_f32_16x16x32_bf16 v[50:53], v[154:157], v[162:165], v[50:53]
	v_mfma_f32_16x16x32_bf16 v[38:41], v[146:149], v[194:197], v[38:41]
	v_mfma_f32_16x16x32_bf16 v[34:37], v[154:157], v[194:197], v[34:37]
	v_mfma_f32_16x16x32_bf16 v[22:25], v[146:149], v[202:205], v[22:25]
	v_mfma_f32_16x16x32_bf16 v[18:21], v[154:157], v[202:205], v[18:21]
	v_mfma_f32_16x16x32_bf16 v[6:9], v[146:149], v[218:221], v[6:9]
	v_mfma_f32_16x16x32_bf16 v[2:5], v[154:157], v[218:221], v[2:5]
	v_mfma_f32_16x16x32_bf16 v[54:57], v[150:153], v[166:169], v[54:57]
	v_mfma_f32_16x16x32_bf16 v[50:53], v[158:161], v[166:169], v[50:53]
	v_mfma_f32_16x16x32_bf16 v[38:41], v[150:153], v[198:201], v[38:41]
	v_mfma_f32_16x16x32_bf16 v[34:37], v[158:161], v[198:201], v[34:37]
	v_mfma_f32_16x16x32_bf16 v[22:25], v[150:153], v[206:209], v[22:25]
	v_mfma_f32_16x16x32_bf16 v[18:21], v[158:161], v[206:209], v[18:21]
	v_mfma_f32_16x16x32_bf16 v[6:9], v[150:153], v[222:225], v[6:9]
	v_mfma_f32_16x16x32_bf16 v[2:5], v[158:161], v[222:225], v[2:5]
